# conv item epilogue: the 64 two-byte result stores per lane paired into 32 dword stores (quad_perm DPP neighbour exchange + v_perm_b32; odd lanes store row i+1 at base+14)
# baseline (speedup 1.0000x reference)
.LBB0_907:
	v_and_b32_e32 v252, 1, v160
	v_sub_u32_e32 v255, 0, v252
	s_mov_b32 s98, 0x3020706
	v_mov_b32_e32 v211, 0x5040100
	v_bfi_b32 v211, v255, s98, v211
	v_mul_u32_u24_e32 v252, 14, v252
	v_mov_b32_e32 v253, 0
	v_lshl_add_u64 v[2:3], s[40:41], 1, v[176:177]
	v_lshl_add_u64 v[2:3], v[2:3], 0, v[252:253]
	v_mov_b32_e32 v183, v0
	v_lshl_add_u64 v[4:5], v[2:3], 0, v[182:183]
	v_mov_b32_e32 v185, v0
	v_lshl_add_u64 v[6:7], v[4:5], 0, v[184:185]
	v_mov_b32_e32 v187, v0
	v_cvt_pk_bf16_f32 v1, v128, v129
	v_lshl_add_u64 v[6:7], v[6:7], 0, v[186:187]
	s_nop 1
	v_mov_b32_dpp v255, v1 quad_perm:[1,0,3,2] row_mask:0xf bank_mask:0xf
	v_perm_b32 v255, v255, v1, v211
	global_store_dword v[6:7], v255, off
	v_cvt_pk_bf16_f32 v1, v130, v131
	s_nop 1
	v_mov_b32_dpp v255, v1 quad_perm:[1,0,3,2] row_mask:0xf bank_mask:0xf
	v_perm_b32 v255, v255, v1, v211
	global_store_dword v[6:7], v255, off offset:32
	v_cvt_pk_bf16_f32 v1, v132, v133
	s_nop 1
	v_mov_b32_dpp v255, v1 quad_perm:[1,0,3,2] row_mask:0xf bank_mask:0xf
	v_perm_b32 v255, v255, v1, v211
	global_store_dword v[6:7], v255, off offset:128
	v_cvt_pk_bf16_f32 v1, v134, v135
	s_nop 1
	v_mov_b32_dpp v255, v1 quad_perm:[1,0,3,2] row_mask:0xf bank_mask:0xf
	v_perm_b32 v255, v255, v1, v211
	global_store_dword v[6:7], v255, off offset:160
	v_cvt_pk_bf16_f32 v1, v136, v137
	s_nop 1
	v_mov_b32_dpp v255, v1 quad_perm:[1,0,3,2] row_mask:0xf bank_mask:0xf
	v_perm_b32 v255, v255, v1, v211
	global_store_dword v[6:7], v255, off offset:256
	v_cvt_pk_bf16_f32 v1, v138, v139
	s_nop 1
	v_mov_b32_dpp v255, v1 quad_perm:[1,0,3,2] row_mask:0xf bank_mask:0xf
	v_perm_b32 v255, v255, v1, v211
	global_store_dword v[6:7], v255, off offset:288
	v_cvt_pk_bf16_f32 v1, v140, v141
	v_mov_b32_e32 v189, v0
	s_nop 1
	v_mov_b32_dpp v255, v1 quad_perm:[1,0,3,2] row_mask:0xf bank_mask:0xf
	v_perm_b32 v255, v255, v1, v211
	global_store_dword v[6:7], v255, off offset:384
	v_cvt_pk_bf16_f32 v1, v142, v143
	v_lshl_add_u64 v[4:5], v[4:5], 0, v[188:189]
	s_nop 1
	v_mov_b32_dpp v255, v1 quad_perm:[1,0,3,2] row_mask:0xf bank_mask:0xf
	v_perm_b32 v255, v255, v1, v211
	global_store_dword v[6:7], v255, off offset:416
	v_cvt_pk_bf16_f32 v1, v112, v113
	v_lshl_add_u64 v[4:5], v[4:5], 0, v[186:187]
	s_nop 1
	v_mov_b32_dpp v255, v1 quad_perm:[1,0,3,2] row_mask:0xf bank_mask:0xf
	v_perm_b32 v255, v255, v1, v211
	global_store_dword v[4:5], v255, off
	v_cvt_pk_bf16_f32 v1, v114, v115
	s_nop 1
	v_mov_b32_dpp v255, v1 quad_perm:[1,0,3,2] row_mask:0xf bank_mask:0xf
	v_perm_b32 v255, v255, v1, v211
	global_store_dword v[4:5], v255, off offset:32
	v_cvt_pk_bf16_f32 v1, v116, v117
	s_nop 1
	v_mov_b32_dpp v255, v1 quad_perm:[1,0,3,2] row_mask:0xf bank_mask:0xf
	v_perm_b32 v255, v255, v1, v211
	global_store_dword v[4:5], v255, off offset:128
	v_cvt_pk_bf16_f32 v1, v118, v119
	s_nop 1
	v_mov_b32_dpp v255, v1 quad_perm:[1,0,3,2] row_mask:0xf bank_mask:0xf
	v_perm_b32 v255, v255, v1, v211
	global_store_dword v[4:5], v255, off offset:160
	v_cvt_pk_bf16_f32 v1, v120, v121
	s_nop 1
	v_mov_b32_dpp v255, v1 quad_perm:[1,0,3,2] row_mask:0xf bank_mask:0xf
	v_perm_b32 v255, v255, v1, v211
	global_store_dword v[4:5], v255, off offset:256
	v_cvt_pk_bf16_f32 v1, v122, v123
	s_nop 1
	v_mov_b32_dpp v255, v1 quad_perm:[1,0,3,2] row_mask:0xf bank_mask:0xf
	v_perm_b32 v255, v255, v1, v211
	global_store_dword v[4:5], v255, off offset:288
	v_cvt_pk_bf16_f32 v1, v124, v125
	v_mov_b32_e32 v191, v0
	s_nop 1
	v_mov_b32_dpp v255, v1 quad_perm:[1,0,3,2] row_mask:0xf bank_mask:0xf
	v_perm_b32 v255, v255, v1, v211
	global_store_dword v[4:5], v255, off offset:384
	v_cvt_pk_bf16_f32 v1, v126, v127
	v_lshl_add_u64 v[2:3], v[2:3], 0, v[190:191]
	s_nop 1
	v_mov_b32_dpp v255, v1 quad_perm:[1,0,3,2] row_mask:0xf bank_mask:0xf
	v_perm_b32 v255, v255, v1, v211
	global_store_dword v[4:5], v255, off offset:416
	v_lshl_add_u64 v[4:5], v[2:3], 0, v[184:185]
	v_cvt_pk_bf16_f32 v1, v96, v97
	v_lshl_add_u64 v[4:5], v[4:5], 0, v[186:187]
	s_nop 1
	v_mov_b32_dpp v255, v1 quad_perm:[1,0,3,2] row_mask:0xf bank_mask:0xf
	v_perm_b32 v255, v255, v1, v211
	global_store_dword v[4:5], v255, off
	v_cvt_pk_bf16_f32 v1, v98, v99
	s_nop 1
	v_mov_b32_dpp v255, v1 quad_perm:[1,0,3,2] row_mask:0xf bank_mask:0xf
	v_perm_b32 v255, v255, v1, v211
	global_store_dword v[4:5], v255, off offset:32
	v_cvt_pk_bf16_f32 v1, v100, v101
	s_nop 1
	v_mov_b32_dpp v255, v1 quad_perm:[1,0,3,2] row_mask:0xf bank_mask:0xf
	v_perm_b32 v255, v255, v1, v211
	global_store_dword v[4:5], v255, off offset:128
	v_cvt_pk_bf16_f32 v1, v102, v103
	s_nop 1
	v_mov_b32_dpp v255, v1 quad_perm:[1,0,3,2] row_mask:0xf bank_mask:0xf
	v_perm_b32 v255, v255, v1, v211
	global_store_dword v[4:5], v255, off offset:160
	v_cvt_pk_bf16_f32 v1, v104, v105
	s_nop 1
	v_mov_b32_dpp v255, v1 quad_perm:[1,0,3,2] row_mask:0xf bank_mask:0xf
	v_perm_b32 v255, v255, v1, v211
	global_store_dword v[4:5], v255, off offset:256
	v_cvt_pk_bf16_f32 v1, v106, v107
	s_nop 1
	v_mov_b32_dpp v255, v1 quad_perm:[1,0,3,2] row_mask:0xf bank_mask:0xf
	v_perm_b32 v255, v255, v1, v211
	global_store_dword v[4:5], v255, off offset:288
	v_cvt_pk_bf16_f32 v1, v108, v109
	s_nop 1
	v_mov_b32_dpp v255, v1 quad_perm:[1,0,3,2] row_mask:0xf bank_mask:0xf
	v_perm_b32 v255, v255, v1, v211
	global_store_dword v[4:5], v255, off offset:384
	v_cvt_pk_bf16_f32 v1, v110, v111
	v_lshl_add_u64 v[2:3], v[2:3], 0, v[188:189]
	s_nop 1
	v_mov_b32_dpp v255, v1 quad_perm:[1,0,3,2] row_mask:0xf bank_mask:0xf
	v_perm_b32 v255, v255, v1, v211
	global_store_dword v[4:5], v255, off offset:416
	v_cvt_pk_bf16_f32 v1, v80, v81
	v_lshl_add_u64 v[2:3], v[2:3], 0, v[186:187]
	s_nop 1
	v_mov_b32_dpp v255, v1 quad_perm:[1,0,3,2] row_mask:0xf bank_mask:0xf
	v_perm_b32 v255, v255, v1, v211
	global_store_dword v[2:3], v255, off
	v_cvt_pk_bf16_f32 v1, v82, v83
	s_nop 1
	v_mov_b32_dpp v255, v1 quad_perm:[1,0,3,2] row_mask:0xf bank_mask:0xf
	v_perm_b32 v255, v255, v1, v211
	global_store_dword v[2:3], v255, off offset:32
	v_cvt_pk_bf16_f32 v1, v84, v85
	s_nop 1
	v_mov_b32_dpp v255, v1 quad_perm:[1,0,3,2] row_mask:0xf bank_mask:0xf
	v_perm_b32 v255, v255, v1, v211
	global_store_dword v[2:3], v255, off offset:128
	v_cvt_pk_bf16_f32 v1, v86, v87
	s_nop 1
	v_mov_b32_dpp v255, v1 quad_perm:[1,0,3,2] row_mask:0xf bank_mask:0xf
	v_perm_b32 v255, v255, v1, v211
	global_store_dword v[2:3], v255, off offset:160
	v_cvt_pk_bf16_f32 v1, v88, v89
	s_nop 1
	v_mov_b32_dpp v255, v1 quad_perm:[1,0,3,2] row_mask:0xf bank_mask:0xf
	v_perm_b32 v255, v255, v1, v211
	global_store_dword v[2:3], v255, off offset:256
	v_cvt_pk_bf16_f32 v1, v90, v91
	s_nop 1
	v_mov_b32_dpp v255, v1 quad_perm:[1,0,3,2] row_mask:0xf bank_mask:0xf
	v_perm_b32 v255, v255, v1, v211
	global_store_dword v[2:3], v255, off offset:288
	v_cvt_pk_bf16_f32 v1, v92, v93
	s_nop 1
	v_mov_b32_dpp v255, v1 quad_perm:[1,0,3,2] row_mask:0xf bank_mask:0xf
	v_perm_b32 v255, v255, v1, v211
	global_store_dword v[2:3], v255, off offset:384
	v_cvt_pk_bf16_f32 v1, v94, v95
	s_nop 1
	v_mov_b32_dpp v255, v1 quad_perm:[1,0,3,2] row_mask:0xf bank_mask:0xf
	v_perm_b32 v255, v255, v1, v211
	global_store_dword v[2:3], v255, off offset:416
	s_waitcnt lgkmcnt(0)
	s_barrier
	s_add_i32 s38, s38, s34
	s_cmpk_lt_i32 s38, 0x200
	s_cbranch_scc0 .LBB0_945
